# v112 with the three FoX-first XCDs chosen as 0,1,2 (adjacent) instead of 0,3,6
# baseline (speedup 1.0000x reference)
; #define LAS __attribute__((address_space(3)))
;     LAS int* sitem = (LAS int*)(lds + ITEM_OFF);
;     constexpr int N_D = 256, N_B = 2048, N_A = 128, N_C = 128, N_ALL = N_D + N_B + N_A + N_C;
;     const int pref = ((__builtin_amdgcn_s_getreg((3 << 11) | 20) & 3u) != 0u) ? 1 : 0;
;     auto fetch = [&]() -> int {
;         auto q1 = [&](int i) -> int { return i < N_A + N_C ? N_D + N_B + i : N_D + (i - (N_A + N_C)); };
;         if (pref == 0) { int i = (int)atomicAdd(ctr, 1u); if (i < N_D) return i; i = (int)atomicAdd(ctr + 32, 1u); return i < N_ALL - N_D ? q1(i) : N_ALL; }
;         int i = (int)atomicAdd(ctr + 32, 1u); if (i < N_ALL - N_D) return q1(i); i = (int)atomicAdd(ctr, 1u); return i < N_D ? i : N_ALL; };
;     int nxt = 0;
;     if (threadIdx.x == 0) nxt = fetch();
.LBB0_112:
	v_readlane_b32 s0, v253, 49
	v_readlane_b32 s1, v253, 50
	s_lshl_b32 s0, s0, 1
	v_readlane_b32 s1, v253, 51
	s_add_i32 s0, s0, s1
	s_ashr_i32 s1, s0, 31
	v_readlane_b32 s20, v251, 1
	s_lshl_b64 s[0:1], s[0:1], 2
	v_readlane_b32 s22, v251, 3
	v_readlane_b32 s23, v251, 4
	s_add_u32 s0, s22, s0
	s_addc_u32 s1, s23, s1
	v_writelane_b32 v253, s0, 55
	v_mov_b32_e32 v180, 0
	v_readlane_b32 s21, v251, 2
	v_writelane_b32 v253, s1, 56
	s_getreg_b32 s0, hwreg(HW_REG_XCC_ID, 0, 4)
	s_lshr_b32 s0, 0x07, s0
	s_and_b32 s0, s0, 1
	s_cmp_eq_u32 s0, 0
	s_cselect_b64 s[0:1], -1, 0
	v_writelane_b32 v253, s0, 57
	v_readlane_b32 s24, v251, 5
	v_readlane_b32 s25, v251, 6
	v_writelane_b32 v253, s1, 58
	v_readlane_b32 s26, v251, 7
	v_readlane_b32 s27, v251, 8
	s_mov_b64 s[0:1], exec
	v_readlane_b32 s20, v251, 13
	v_readlane_b32 s21, v251, 14
	s_and_b64 s[20:21], s[0:1], s[20:21]
	s_mov_b64 exec, s[20:21]
	s_cbranch_execz .LBB0_131
	v_readlane_b32 s20, v253, 57
	v_readlane_b32 s21, v253, 58
	s_and_b64 vcc, exec, s[20:21]
	s_cbranch_vccz .LBB0_123
	s_mov_b64 s[22:23], exec
	v_mbcnt_lo_u32_b32 v0, s22, 0
	v_mbcnt_hi_u32_b32 v0, s23, v0
	v_cmp_eq_u32_e32 vcc, 0, v0
	s_and_saveexec_b64 s[20:21], vcc
	s_cbranch_execz .LBB0_116
	s_bcnt1_i32_b64 s22, s[22:23]
	v_mov_b32_e32 v2, s22
	v_readlane_b32 s22, v253, 55
	v_readlane_b32 s23, v253, 56
	s_nop 4
	global_atomic_add v2, v1, v2, s[22:23] offset:128 sc0
